# diff attention prompt loop: static s_setprio 1 for the younger wave half (waves 4-7) instead of the s_sleep stagger
# speedup vs baseline: 1.0018x; 1.0012x over previous
; #define LAS __attribute__((address_space(3)))
; __device__ __forceinline__ void df_attn_phase(int j, float lambda_init, LAS unsigned char* lds, unsigned* ctr) {
;     ...
;                 *(LAS u32x4*)(lds + kofs) = ka0; *(LAS u32x4*)(lds + kofs + 32 * AT_KPITCH) = ka1; *(LAS u32x4*)(lds + vofs) = va0; *(LAS u32x4*)(lds + vofs + 32 * 64) = va1;
;                 *(LAS u32x4*)(lds + AT_BUF + kofs) = kb0; *(LAS u32x4*)(lds + AT_BUF + kofs + 32 * AT_KPITCH) = kb1; *(LAS u32x4*)(lds + AT_BUF + vofs) = vb0; *(LAS u32x4*)(lds + AT_BUF + vofs + 32 * 64) = vb1;
;                 __syncthreads();
;                 if (t + 2 < ntile) { const size_t off = (size_t)(t + 2) * 64 * 1024;
;                     ka0 = *(const u32x4*)(kg + off); ka1 = *(const u32x4*)(kg + off + 32 * 1024); va0 = *(const u32x4*)(vg + off); va1 = *(const u32x4*)(vg + off + 32 * 1024);
;                     kb0 = *(const u32x4*)(kg + off + 64 * 1024); kb1 = *(const u32x4*)(kg + off + 96 * 1024); vb0 = *(const u32x4*)(vg + off + 64 * 1024); vb1 = *(const u32x4*)(vg + off + 96 * 1024); }
;                 if (t <= my_top) df_tile<LdsProv, false>(L0, comp, qf, 64 * t, 0, lane, mx, ls, o);
.LBB0_266:
	s_cmp_ge_u32 s36, s30
	s_cselect_b64 s[6:7], -1, 0
	s_and_b64 vcc, exec, s[6:7]
	s_waitcnt vmcnt(7)
	ds_write_b128 v214, v[112:115]
	s_waitcnt vmcnt(5)
	ds_write_b128 v214, v[116:119] offset:4608
	ds_write_b128 v215, v[120:123] offset:18432
	s_waitcnt vmcnt(4)
	ds_write_b128 v215, v[124:127] offset:20480
	s_waitcnt vmcnt(3)
	ds_write_b128 v214, v[128:131] offset:34816
	s_waitcnt vmcnt(2)
	ds_write_b128 v214, v[132:135] offset:39424
	s_waitcnt vmcnt(1)
	ds_write_b128 v215, v[136:139] offset:53248
	s_waitcnt vmcnt(0)
	ds_write_b128 v215, v[140:143] offset:55296
	s_waitcnt lgkmcnt(0)
	s_barrier
	s_cmp_eq_u32 s22, 0
	s_cbranch_scc1 .Ldf_nostag
	s_setprio 1
